# FFN-up GEMM: the two wave halves stay one segment apart across the unit boundary (epilogue alignment barriers removed, one balancing barrier at phase end) so each half's relu^2 epilogue overlaps the o
# baseline (speedup 1.0000x reference)
; __device__ __forceinline__ float sigmoidf_(float x) { return __builtin_amdgcn_rcpf(1.0f + __builtin_amdgcn_exp2f(x * (-1.4426950409f))); }
; #define PG8_BAR __builtin_amdgcn_s_barrier()
; __device__ __forceinline__ unsigned pk2(float lo, float hi) { return pg8::cvt_pk_bf16(lo, hi); }
; template <class Epi, class Sched, bool ALIGN_EPI = true>
; __device__ __forceinline__ void gemm_phase(PG8_LAS unsigned char* lds, const int K, const Sched& S, const Epi& E) {
;     ...
;         if constexpr (ALIGN_EPI) { if (wr == 0) PG8_BAR; }
;     bf16* base = O + (row0 + wr * 64 + fr) * ld + col0 + wc * 32 + 8 * fq;
; #pragma unroll
;     for (int ai = 0; ai < 2; ++ai)
; #pragma unroll
;         for (int m = 0; m < 4; ++m) { bf16* rowp = base + (size_t)(ai * 128 + m * 16) * ld;
; #pragma unroll
;             for (int bj = 0; bj < 2; ++bj) { pg8::f32x4 v0 = acc[ai][bj][m][0], v1 = acc[ai][bj][m][1];
; #pragma unroll
;                 for (int e = 0; e < 4; ++e) {
;                     if (ACT == 1) { v0[e] = pg8::gelu_tanh(v0[e]); v1[e] = pg8::gelu_tanh(v1[e]); }
;                     if (ACT == 2) { v0[e] = pg8::sigmoidf_(v0[e]); v1[e] = pg8::sigmoidf_(v1[e]); }
;                     if (ACT == 3) { const int i0 = __float_as_int(v0[e]), i1 = __float_as_int(v1[e]);
;                         const float a0 = __int_as_float(i0 > 0 ? i0 : 0), a1 = __int_as_float(i1 > 0 ? i1 : 0); v0[e] = a0 * a0; v1[e] = a1 * a1; } }
;                 v4u w; w.x = pk2(v0[0], v0[1]); w.y = pk2(v0[2], v0[3]); w.z = pk2(v1[0], v1[1]); w.w = pk2(v1[2], v1[3]);
;                 *(v4u*)(rowp + bj * bjstride) = w; } }
; }
.Lkexit_3:
	s_and_b64 vcc, exec, s[12:13]
	s_branch .LBB0_1716
	s_barrier
.LBB0_1716:
	s_ashr_i32 s23, s22, 31
	s_ashr_i32 s25, s24, 31
	s_lshl_b64 s[22:23], s[22:23], 21
	v_lshl_add_u64 v[150:151], v[140:141], 0, s[22:23]
	s_lshl_b64 s[22:23], s[24:25], 9
	v_max_i32_e32 v122, 0, v122
	v_max_i32_e32 v123, 0, v123
	v_max_i32_e32 v124, 0, v124
	v_lshl_add_u64 v[150:151], v[150:151], 0, s[22:23]
	v_max_i32_e32 v126, 0, v126
	v_mul_f32_e32 v155, v122, v122
	v_max_i32_e32 v122, 0, v127
	v_mul_f32_e32 v127, v123, v123
	v_max_i32_e32 v123, 0, v128
	v_mul_f32_e32 v128, v124, v124
	v_max_i32_e32 v124, 0, v129
	v_max_i32_e32 v125, 0, v125
	v_lshl_add_u64 v[150:151], v[150:151], 0, s[6:7]
	v_mul_f32_e32 v126, v126, v126
	v_mul_f32_e32 v122, v122, v122
	v_mul_f32_e32 v123, v123, v123
	v_mul_f32_e32 v124, v124, v124
	v_mul_f32_e32 v125, v125, v125
	v_lshl_add_u64 v[150:151], v[150:151], 0, v[138:139]
	v_cvt_pk_bf16_f32 v122, v126, v122
	v_cvt_pk_bf16_f32 v123, v123, v124
	v_cvt_pk_bf16_f32 v124, v155, v127
	v_cvt_pk_bf16_f32 v125, v128, v125
	v_max_i32_e32 v110, 0, v110
	v_max_i32_e32 v111, 0, v111
	v_max_i32_e32 v112, 0, v112
	global_store_dwordx4 v[150:151], v[122:125], off
	v_max_i32_e32 v118, 0, v118
	v_max_i32_e32 v113, 0, v113
	v_mul_f32_e32 v122, v110, v110
	v_max_i32_e32 v110, 0, v119
	v_mul_f32_e32 v119, v111, v111
	v_max_i32_e32 v111, 0, v120
	v_mul_f32_e32 v120, v112, v112
	v_max_i32_e32 v112, 0, v121
	v_mul_f32_e32 v118, v118, v118
	v_mul_f32_e32 v110, v110, v110
	v_mul_f32_e32 v111, v111, v111
	v_mul_f32_e32 v112, v112, v112
	v_mul_f32_e32 v113, v113, v113
	v_cvt_pk_bf16_f32 v110, v118, v110
	v_cvt_pk_bf16_f32 v111, v111, v112
	v_cvt_pk_bf16_f32 v112, v122, v119
	v_cvt_pk_bf16_f32 v113, v120, v113
	v_max_i32_e32 v106, 0, v106
	global_store_dwordx4 v[150:151], v[110:113], off offset:256
	v_max_i32_e32 v107, 0, v107
	v_max_i32_e32 v108, 0, v108
	v_max_i32_e32 v110, 0, v114
	v_mul_f32_e32 v111, v106, v106
	v_max_i32_e32 v106, 0, v115
	v_mul_f32_e32 v110, v110, v110
	v_mul_f32_e32 v106, v106, v106
	v_mul_f32_e32 v112, v107, v107
	v_max_i32_e32 v107, 0, v116
	v_mul_f32_e32 v113, v108, v108
	v_max_i32_e32 v108, 0, v117
	v_max_i32_e32 v109, 0, v109
	v_mul_f32_e32 v107, v107, v107
	v_mul_f32_e32 v108, v108, v108
	v_mul_f32_e32 v109, v109, v109
	v_cvt_pk_bf16_f32 v106, v110, v106
	v_add_co_u32_e32 v110, vcc, s58, v150
	v_cvt_pk_bf16_f32 v107, v107, v108
	v_cvt_pk_bf16_f32 v108, v111, v112
	v_cvt_pk_bf16_f32 v109, v113, v109
	v_addc_co_u32_e32 v111, vcc, 0, v151, vcc
	v_max_i32_e32 v94, 0, v94
	v_max_i32_e32 v95, 0, v95
	v_max_i32_e32 v96, 0, v96
	global_store_dwordx4 v[110:111], v[106:109], off
	v_max_i32_e32 v102, 0, v102
	v_max_i32_e32 v97, 0, v97
	v_mul_f32_e32 v106, v94, v94
	v_max_i32_e32 v94, 0, v103
	v_mul_f32_e32 v103, v95, v95
	v_max_i32_e32 v95, 0, v104
	v_mul_f32_e32 v104, v96, v96
	v_max_i32_e32 v96, 0, v105
	v_mul_f32_e32 v102, v102, v102
	v_mul_f32_e32 v94, v94, v94
	v_mul_f32_e32 v95, v95, v95
	v_mul_f32_e32 v96, v96, v96
	v_mul_f32_e32 v97, v97, v97
	v_cvt_pk_bf16_f32 v94, v102, v94
	v_cvt_pk_bf16_f32 v95, v95, v96
	v_cvt_pk_bf16_f32 v96, v106, v103
	v_cvt_pk_bf16_f32 v97, v104, v97
	v_max_i32_e32 v90, 0, v90
	global_store_dwordx4 v[110:111], v[94:97], off offset:256
	v_max_i32_e32 v91, 0, v91
	v_max_i32_e32 v92, 0, v92
	v_max_i32_e32 v94, 0, v98
	v_mul_f32_e32 v95, v90, v90
	v_max_i32_e32 v90, 0, v99
	v_mul_f32_e32 v94, v94, v94
	v_mul_f32_e32 v90, v90, v90
	v_mul_f32_e32 v96, v91, v91
	v_max_i32_e32 v91, 0, v100
	v_mul_f32_e32 v97, v92, v92
	v_max_i32_e32 v92, 0, v101
	v_max_i32_e32 v93, 0, v93
	v_mul_f32_e32 v91, v91, v91
	v_mul_f32_e32 v92, v92, v92
	v_mul_f32_e32 v93, v93, v93
	v_cvt_pk_bf16_f32 v90, v94, v90
	v_add_co_u32_e32 v94, vcc, s59, v150
	v_cvt_pk_bf16_f32 v91, v91, v92
	v_cvt_pk_bf16_f32 v92, v95, v96
	v_cvt_pk_bf16_f32 v93, v97, v93
	v_addc_co_u32_e32 v95, vcc, 0, v151, vcc
	v_max_i32_e32 v78, 0, v78
	v_max_i32_e32 v79, 0, v79
	v_max_i32_e32 v80, 0, v80
	global_store_dwordx4 v[94:95], v[90:93], off
	v_max_i32_e32 v86, 0, v86
	v_max_i32_e32 v81, 0, v81
	v_mul_f32_e32 v90, v78, v78
	v_max_i32_e32 v78, 0, v87
	v_mul_f32_e32 v87, v79, v79
	v_max_i32_e32 v79, 0, v88
	v_mul_f32_e32 v88, v80, v80
	v_max_i32_e32 v80, 0, v89
	v_mul_f32_e32 v86, v86, v86
	v_mul_f32_e32 v78, v78, v78
	v_mul_f32_e32 v79, v79, v79
	v_mul_f32_e32 v80, v80, v80
	v_mul_f32_e32 v81, v81, v81
	v_cvt_pk_bf16_f32 v78, v86, v78
	v_cvt_pk_bf16_f32 v79, v79, v80
	v_cvt_pk_bf16_f32 v80, v90, v87
	v_cvt_pk_bf16_f32 v81, v88, v81
	v_max_i32_e32 v74, 0, v74
	global_store_dwordx4 v[94:95], v[78:81], off offset:256
	v_max_i32_e32 v75, 0, v75
	v_max_i32_e32 v76, 0, v76
	v_max_i32_e32 v78, 0, v82
	v_mul_f32_e32 v79, v74, v74
	v_max_i32_e32 v74, 0, v83
	v_mul_f32_e32 v78, v78, v78
	v_mul_f32_e32 v74, v74, v74
	v_mul_f32_e32 v80, v75, v75
	v_max_i32_e32 v75, 0, v84
	v_mul_f32_e32 v81, v76, v76
	v_max_i32_e32 v76, 0, v85
	v_max_i32_e32 v77, 0, v77
	v_mul_f32_e32 v75, v75, v75
	v_mul_f32_e32 v76, v76, v76
	v_mul_f32_e32 v77, v77, v77
	v_cvt_pk_bf16_f32 v74, v78, v74
	v_add_co_u32_e32 v78, vcc, s60, v150
	v_cvt_pk_bf16_f32 v75, v75, v76
	v_cvt_pk_bf16_f32 v76, v79, v80
	v_cvt_pk_bf16_f32 v77, v81, v77
	v_addc_co_u32_e32 v79, vcc, 0, v151, vcc
	v_max_i32_e32 v66, 0, v66
	v_max_i32_e32 v67, 0, v67
	v_max_i32_e32 v68, 0, v68
	global_store_dwordx4 v[78:79], v[74:77], off
	v_max_i32_e32 v70, 0, v70
	v_max_i32_e32 v69, 0, v69
	v_mul_f32_e32 v74, v66, v66
	v_max_i32_e32 v66, 0, v71
	v_mul_f32_e32 v71, v67, v67
	v_max_i32_e32 v67, 0, v72
	v_mul_f32_e32 v72, v68, v68
	v_max_i32_e32 v68, 0, v73
	v_mul_f32_e32 v70, v70, v70
	v_mul_f32_e32 v66, v66, v66
	v_mul_f32_e32 v67, v67, v67
; __device__ __forceinline__ float sigmoidf_(float x) { return __builtin_amdgcn_rcpf(1.0f + __builtin_amdgcn_exp2f(x * (-1.4426950409f))); }
; #define PG8_WAIT_V(n) asm volatile("s_waitcnt vmcnt(" #n ")" ::: "memory")
; #define PG8_BAR __builtin_amdgcn_s_barrier()
; __device__ __forceinline__ unsigned pk2(float lo, float hi) { return pg8::cvt_pk_bf16(lo, hi); }
; template <class Epi, class Sched, bool ALIGN_EPI = true>
; __device__ __forceinline__ void gemm_phase(PG8_LAS unsigned char* lds, const int K, const Sched& S, const Epi& E) {
;     ...
;         if constexpr (ALIGN_EPI) { if (wr == 1) PG8_BAR; }
;     }
;     PG8_WAIT_V(0);
;     if constexpr (!ALIGN_EPI) { if (wr == 0) PG8_BAR; }
;     PG8_BAR;
;     bf16* base = O + (row0 + wr * 64 + fr) * ld + col0 + wc * 32 + 8 * fq;
; #pragma unroll
;     for (int ai = 0; ai < 2; ++ai)
; #pragma unroll
;         for (int m = 0; m < 4; ++m) { bf16* rowp = base + (size_t)(ai * 128 + m * 16) * ld;
; #pragma unroll
;             for (int bj = 0; bj < 2; ++bj) { pg8::f32x4 v0 = acc[ai][bj][m][0], v1 = acc[ai][bj][m][1];
; #pragma unroll
;                 for (int e = 0; e < 4; ++e) {
;                     if (ACT == 1) { v0[e] = pg8::gelu_tanh(v0[e]); v1[e] = pg8::gelu_tanh(v1[e]); }
;                     if (ACT == 2) { v0[e] = pg8::sigmoidf_(v0[e]); v1[e] = pg8::sigmoidf_(v1[e]); }
;                     if (ACT == 3) { const int i0 = __float_as_int(v0[e]), i1 = __float_as_int(v1[e]);
;                         const float a0 = __int_as_float(i0 > 0 ? i0 : 0), a1 = __int_as_float(i1 > 0 ? i1 : 0); v0[e] = a0 * a0; v1[e] = a1 * a1; } }
;                 v4u w; w.x = pk2(v0[0], v0[1]); w.y = pk2(v0[2], v0[3]); w.z = pk2(v1[0], v1[1]); w.w = pk2(v1[2], v1[3]);
;                 *(v4u*)(rowp + bj * bjstride) = w; } }
; }
	v_mul_f32_e32 v68, v68, v68
	v_mul_f32_e32 v69, v69, v69
	v_cvt_pk_bf16_f32 v66, v70, v66
	v_cvt_pk_bf16_f32 v67, v67, v68
	v_cvt_pk_bf16_f32 v68, v74, v71
	v_cvt_pk_bf16_f32 v69, v72, v69
	v_max_i32_e32 v58, 0, v58
	global_store_dwordx4 v[78:79], v[66:69], off offset:256
	v_max_i32_e32 v62, 0, v62
	v_max_i32_e32 v59, 0, v59
	v_mul_f32_e32 v66, v58, v58
	v_max_i32_e32 v58, 0, v63
	v_max_i32_e32 v60, 0, v60
	v_mul_f32_e32 v62, v62, v62
	v_mul_f32_e32 v58, v58, v58
	v_mul_f32_e32 v63, v59, v59
	v_max_i32_e32 v59, 0, v64
	v_mul_f32_e32 v64, v60, v60
	v_max_i32_e32 v60, 0, v65
	v_max_i32_e32 v61, 0, v61
	v_mul_f32_e32 v59, v59, v59
	v_mul_f32_e32 v60, v60, v60
	v_mul_f32_e32 v61, v61, v61
	v_cvt_pk_bf16_f32 v58, v62, v58
	v_add_co_u32_e32 v62, vcc, s61, v150
	v_cvt_pk_bf16_f32 v59, v59, v60
	v_cvt_pk_bf16_f32 v60, v66, v63
	v_cvt_pk_bf16_f32 v61, v64, v61
	v_addc_co_u32_e32 v63, vcc, 0, v151, vcc
	v_max_i32_e32 v46, 0, v46
	v_max_i32_e32 v47, 0, v47
	v_max_i32_e32 v48, 0, v48
	global_store_dwordx4 v[62:63], v[58:61], off
	v_max_i32_e32 v54, 0, v54
	v_max_i32_e32 v49, 0, v49
	v_mul_f32_e32 v58, v46, v46
	v_max_i32_e32 v46, 0, v55
	v_mul_f32_e32 v55, v47, v47
	v_max_i32_e32 v47, 0, v56
	v_mul_f32_e32 v56, v48, v48
	v_max_i32_e32 v48, 0, v57
	v_mul_f32_e32 v54, v54, v54
	v_mul_f32_e32 v46, v46, v46
	v_mul_f32_e32 v47, v47, v47
	v_mul_f32_e32 v48, v48, v48
	v_mul_f32_e32 v49, v49, v49
	v_cvt_pk_bf16_f32 v46, v54, v46
	v_cvt_pk_bf16_f32 v47, v47, v48
	v_cvt_pk_bf16_f32 v48, v58, v55
	v_cvt_pk_bf16_f32 v49, v56, v49
	v_max_i32_e32 v42, 0, v42
	global_store_dwordx4 v[62:63], v[46:49], off offset:256
	v_max_i32_e32 v43, 0, v43
	v_max_i32_e32 v44, 0, v44
	v_max_i32_e32 v46, 0, v50
	v_mul_f32_e32 v47, v42, v42
	v_max_i32_e32 v42, 0, v51
	v_mul_f32_e32 v46, v46, v46
	v_mul_f32_e32 v42, v42, v42
	v_mul_f32_e32 v48, v43, v43
	v_max_i32_e32 v43, 0, v52
	v_mul_f32_e32 v49, v44, v44
	v_max_i32_e32 v44, 0, v53
	v_max_i32_e32 v45, 0, v45
	v_mul_f32_e32 v43, v43, v43
	v_mul_f32_e32 v44, v44, v44
	v_mul_f32_e32 v45, v45, v45
	v_cvt_pk_bf16_f32 v42, v46, v42
	v_add_co_u32_e32 v46, vcc, s62, v150
	v_cvt_pk_bf16_f32 v43, v43, v44
	v_cvt_pk_bf16_f32 v44, v47, v48
	v_cvt_pk_bf16_f32 v45, v49, v45
	v_addc_co_u32_e32 v47, vcc, 0, v151, vcc
	v_max_i32_e32 v30, 0, v30
	v_max_i32_e32 v31, 0, v31
	v_max_i32_e32 v32, 0, v32
	global_store_dwordx4 v[46:47], v[42:45], off
	v_max_i32_e32 v38, 0, v38
	v_max_i32_e32 v33, 0, v33
	v_mul_f32_e32 v42, v30, v30
	v_max_i32_e32 v30, 0, v39
	v_mul_f32_e32 v39, v31, v31
	v_max_i32_e32 v31, 0, v40
	v_mul_f32_e32 v40, v32, v32
	v_max_i32_e32 v32, 0, v41
	v_mul_f32_e32 v38, v38, v38
	v_mul_f32_e32 v30, v30, v30
	v_mul_f32_e32 v31, v31, v31
	v_mul_f32_e32 v32, v32, v32
	v_mul_f32_e32 v33, v33, v33
	v_cvt_pk_bf16_f32 v30, v38, v30
	v_cvt_pk_bf16_f32 v31, v31, v32
	v_cvt_pk_bf16_f32 v32, v42, v39
	v_cvt_pk_bf16_f32 v33, v40, v33
	v_max_i32_e32 v26, 0, v26
	global_store_dwordx4 v[46:47], v[30:33], off offset:256
	v_max_i32_e32 v27, 0, v27
	v_max_i32_e32 v28, 0, v28
	v_max_i32_e32 v30, 0, v34
	v_mul_f32_e32 v31, v26, v26
	v_max_i32_e32 v26, 0, v35
	v_mul_f32_e32 v30, v30, v30
	v_mul_f32_e32 v26, v26, v26
	v_mul_f32_e32 v32, v27, v27
	v_max_i32_e32 v27, 0, v36
	v_mul_f32_e32 v33, v28, v28
	v_max_i32_e32 v28, 0, v37
	v_max_i32_e32 v29, 0, v29
	v_mul_f32_e32 v27, v27, v27
	v_mul_f32_e32 v28, v28, v28
	v_mul_f32_e32 v29, v29, v29
	v_cvt_pk_bf16_f32 v26, v30, v26
	v_add_co_u32_e32 v30, vcc, s63, v150
	v_cvt_pk_bf16_f32 v27, v27, v28
	v_cvt_pk_bf16_f32 v28, v31, v32
	v_cvt_pk_bf16_f32 v29, v33, v29
	v_addc_co_u32_e32 v31, vcc, 0, v151, vcc
	v_max_i32_e32 v14, 0, v14
	v_max_i32_e32 v15, 0, v15
	v_max_i32_e32 v16, 0, v16
	global_store_dwordx4 v[30:31], v[26:29], off
	v_max_i32_e32 v22, 0, v22
	v_max_i32_e32 v17, 0, v17
	v_mul_f32_e32 v26, v14, v14
	v_max_i32_e32 v14, 0, v23
	v_mul_f32_e32 v23, v15, v15
	v_max_i32_e32 v15, 0, v24
	v_mul_f32_e32 v24, v16, v16
	v_max_i32_e32 v16, 0, v25
	v_mul_f32_e32 v22, v22, v22
	v_mul_f32_e32 v14, v14, v14
	v_mul_f32_e32 v15, v15, v15
	v_mul_f32_e32 v16, v16, v16
	v_mul_f32_e32 v17, v17, v17
	v_cvt_pk_bf16_f32 v14, v22, v14
	v_cvt_pk_bf16_f32 v15, v15, v16
	v_cvt_pk_bf16_f32 v16, v26, v23
	v_cvt_pk_bf16_f32 v17, v24, v17
	v_max_i32_e32 v10, 0, v10
	global_store_dwordx4 v[30:31], v[14:17], off offset:256
	v_max_i32_e32 v11, 0, v11
	v_max_i32_e32 v12, 0, v12
	v_max_i32_e32 v14, 0, v18
	v_mul_f32_e32 v15, v10, v10
	v_max_i32_e32 v10, 0, v19
	v_mul_f32_e32 v14, v14, v14
	v_mul_f32_e32 v10, v10, v10
	v_mul_f32_e32 v16, v11, v11
	v_max_i32_e32 v11, 0, v20
	v_mul_f32_e32 v17, v12, v12
	v_max_i32_e32 v12, 0, v21
	v_max_i32_e32 v13, 0, v13
	v_mul_f32_e32 v11, v11, v11
	v_mul_f32_e32 v12, v12, v12
	v_mul_f32_e32 v13, v13, v13
	v_cvt_pk_bf16_f32 v10, v14, v10
	v_add_co_u32_e32 v14, vcc, s64, v150
	v_cvt_pk_bf16_f32 v11, v11, v12
	v_cvt_pk_bf16_f32 v12, v15, v16
	v_cvt_pk_bf16_f32 v13, v17, v13
	v_addc_co_u32_e32 v15, vcc, 0, v151, vcc
	v_max_i32_e32 v2, 0, v2
	v_max_i32_e32 v3, 0, v3
	v_max_i32_e32 v4, 0, v4
	global_store_dwordx4 v[14:15], v[10:13], off
	v_max_i32_e32 v6, 0, v6
	v_max_i32_e32 v5, 0, v5
	v_mul_f32_e32 v10, v2, v2
	v_max_i32_e32 v2, 0, v7
	v_mul_f32_e32 v7, v3, v3
	v_max_i32_e32 v3, 0, v8
	v_mul_f32_e32 v8, v4, v4
	v_max_i32_e32 v4, 0, v9
	v_mul_f32_e32 v6, v6, v6
	v_mul_f32_e32 v2, v2, v2
	v_mul_f32_e32 v3, v3, v3
	v_mul_f32_e32 v4, v4, v4
	v_mul_f32_e32 v5, v5, v5
	v_cvt_pk_bf16_f32 v2, v6, v2
	v_cvt_pk_bf16_f32 v3, v3, v4
	v_cvt_pk_bf16_f32 v4, v10, v7
	v_cvt_pk_bf16_f32 v5, v8, v5
	s_andn2_b64 vcc, exec, s[0:1]
	s_mov_b64 s[0:1], -1
	global_store_dwordx4 v[14:15], v[2:5], off offset:256
	s_cbranch_vccnz .LBB0_1705
	s_andn2_b64 vcc, exec, s[8:9]
	s_branch .LBB0_1704
	s_barrier
	s_branch .LBB0_1704
.LBB0_1719:
	s_and_b64 vcc, exec, s[12:13]
	s_cbranch_vccz .Lp9_fin
	s_barrier
.Lp9_fin:
	s_waitcnt vmcnt(0)
	s_barrier
